# tk
# speedup vs baseline: 1.0069x; 1.0069x over previous
; DEVI int wave_sum_i(int v) {
; #pragma unroll
;   for (int o = 32; o; o >>= 1) v += __shfl_xor(v, o);
;   return v;
; }
; DEVI void ph_topk(const Params& p, char* shm) {
;     ...
;       unsigned cand = res | (1u << bit);
;       int cnt = 0;
; #pragma unroll
;       for (int i = 0; i < 8; ++i) cnt += (x[i] >= cand) ? 1 : 0;
;       cnt = wave_sum_i(cnt);
;       int* rb = red + (bit & 1) * 8;
;       if (lane == 0) rb[w] = cnt;
.LBB0_1118:
	s_lshl_b32 s2, 1, s5
	v_or_b32_e32 v1, s2, v0
	s_waitcnt vmcnt(0)
	v_cmp_ge_u32_e64 s[2:3], v52, v1
	v_cmp_ge_u32_e64 s[98:99], v54, v1
	s_nop 1
	s_bcnt1_i32_b64 s101, s[2:3]
	s_mov_b32 s100, s101
	s_bcnt1_i32_b64 s101, s[98:99]
	s_add_i32 s100, s100, s101
	v_cmp_ge_u32_e64 s[2:3], v51, v1
	v_cmp_ge_u32_e64 s[98:99], v50, v1
	s_nop 1
	s_bcnt1_i32_b64 s101, s[2:3]
	s_add_i32 s100, s100, s101
	s_bcnt1_i32_b64 s101, s[98:99]
	s_add_i32 s100, s100, s101
	v_cmp_ge_u32_e64 s[2:3], v49, v1
	v_cmp_ge_u32_e64 s[98:99], v48, v1
	s_nop 1
	s_bcnt1_i32_b64 s101, s[2:3]
	s_add_i32 s100, s100, s101
	s_bcnt1_i32_b64 s101, s[98:99]
	s_add_i32 s100, s100, s101
	v_cmp_ge_u32_e64 s[2:3], v47, v1
	v_cmp_ge_u32_e64 s[98:99], v37, v1
	s_nop 1
	s_bcnt1_i32_b64 s101, s[2:3]
	s_add_i32 s100, s100, s101
	s_bcnt1_i32_b64 s101, s[98:99]
	s_add_i32 s100, s100, s101
	v_mov_b32_e32 v2, s100
	s_and_b32 s2, s6, 8
	s_lshl_b32 s2, s2, 2
	s_add_i32 s7, s2, 0
	s_and_saveexec_b64 s[2:3], vcc
	s_cbranch_execz .LBB0_1117
	v_lshl_add_u32 v3, v40, 2, s7
	ds_write_b32 v3, v2
	s_branch .LBB0_1117

; DEVI int wave_sum_i(int v) {
; #pragma unroll
;   for (int o = 32; o; o >>= 1) v += __shfl_xor(v, o);
;   return v;
; }
; DEVI void ph_topk(const Params& p, char* shm) {
;     ...
;       unsigned cand = res | (1u << bit);
;       int cnt = 0;
; #pragma unroll
;       for (int i = 0; i < 8; ++i) cnt += (x[i] >= cand) ? 1 : 0;
;       cnt = wave_sum_i(cnt);
;       int* rb = red + (bit & 1) * 8;
;       if (lane == 0) rb[w] = cnt;
.LBB0_1954:
	s_lshl_b32 s4, 1, s1
	v_or_b32_e32 v1, s4, v0
	s_waitcnt vmcnt(0)
	v_cmp_ge_u32_e64 s[4:5], v52, v1
	v_cmp_ge_u32_e64 s[98:99], v54, v1
	s_nop 1
	s_bcnt1_i32_b64 s101, s[4:5]
	s_mov_b32 s100, s101
	s_bcnt1_i32_b64 s101, s[98:99]
	s_add_i32 s100, s100, s101
	v_cmp_ge_u32_e64 s[4:5], v51, v1
	v_cmp_ge_u32_e64 s[98:99], v50, v1
	s_nop 1
	s_bcnt1_i32_b64 s101, s[4:5]
	s_add_i32 s100, s100, s101
	s_bcnt1_i32_b64 s101, s[98:99]
	s_add_i32 s100, s100, s101
	v_cmp_ge_u32_e64 s[4:5], v49, v1
	v_cmp_ge_u32_e64 s[98:99], v48, v1
	s_nop 1
	s_bcnt1_i32_b64 s101, s[4:5]
	s_add_i32 s100, s100, s101
	s_bcnt1_i32_b64 s101, s[98:99]
	s_add_i32 s100, s100, s101
	v_cmp_ge_u32_e64 s[4:5], v47, v1
	v_cmp_ge_u32_e64 s[98:99], v37, v1
	s_nop 1
	s_bcnt1_i32_b64 s101, s[4:5]
	s_add_i32 s100, s100, s101
	s_bcnt1_i32_b64 s101, s[98:99]
	s_add_i32 s100, s100, s101
	v_mov_b32_e32 v2, s100
	s_and_b32 s4, s6, 8
	s_lshl_b32 s4, s4, 2
	s_add_i32 s7, s4, 0
	s_and_saveexec_b64 s[4:5], vcc
	s_cbranch_execz .LBB0_1953
	v_lshl_add_u32 v3, v40, 2, s7
	ds_write_b32 v3, v2
	s_branch .LBB0_1953
